# NSA selected loop fast path: waves 4-7 defer the second half of each step (softmax hh1 + PV) past the next barrier - SIMD partners half a step out of phase
# speedup vs baseline: 1.0058x; 1.0058x over previous
; template <int MODE, bool FX>
; DI void attn_compute(const int lane, const bf16_t* Ks, const bf16_t* Vs, const bf16x8 (&qf)[2][2], AttnSt& st, const float (&invl)[2],
;                      int lo, int hi, float (&impA)[4], float (&impE)[4], const float CL) {
;     ...
;   for (int ks = 0; ks < 2; ++ks) {
; #pragma unroll
;     for (int kt = 0; kt < 4; ++kt) {
;       int row = kt * 16 + col;
;       bf16x8 kf = *(const bf16x8*)(Ks + row * 64 + (((ks * 4 + quad) ^ ((row >> 1) & 7)) << 3));
; #pragma unroll
;       for (int hh = 0; hh < 2; ++hh) S[kt][hh] = mfma16(kf, qf[hh][ks], S[kt][hh]);
;     }
;   }
;   bf16x8 pf[2][2];
;   const bool full = (lo <= 0) && (hi >= 63);
;   const bool none = (hi < 0) || (lo > 63) || (hi < lo);
;   if (__all(full || none)) {
;     constexpr float L2E = 1.4426950408889634f;
; #pragma unroll
;     for (int hh = 0; hh < 2; ++hh) {
;       float mL;
;       float il = 1.f;
;       if (FX) {
;         mL = full ? CL : 1e30f;
;         if (MODE == 1) il = invl[hh];
;       } else if (MODE != 1) {
;         float mx = -1e30f;
; #pragma unroll
;         for (int kt = 0; kt < 4; ++kt)
; #pragma unroll
;           for (int j = 0; j < 4; ++j) mx = fmaxf(mx, S[kt][hh][j]);
;         mx = full ? mx : -1e30f;
;         mx = fmaxf(mx, shx(mx, 16, lane));
;         mx = fmaxf(mx, shx(mx, 32, lane));
;         const float m_new = fmaxf(st.m[hh], mx);
;         const float alpha = __expf(st.m[hh] - m_new);
;         st.m[hh] = m_new;
;         st.l[hh] *= alpha;
;         if (MODE == 2) {
; #pragma unroll
;           for (int dt = 0; dt < 4; ++dt) st.O[hh][dt] *= alpha;
;         }
;         mL = full ? m_new * L2E : 1e30f;
;       } else {
;         mL = full ? st.m[hh] * L2E : 1e30f;
;         il = invl[hh];
;       }
;       float rs = 0.f;
; #pragma unroll
;       for (int kt = 0; kt < 4; ++kt) {
;         float a = 0.f;
; #pragma unroll
;         for (int j = 0; j < 4; ++j) {
;           float pv = __builtin_amdgcn_exp2f(fmaf(S[kt][hh][j], L2E, -mL));
;           if (MODE == 1) pv *= il;
;           S[kt][hh][j] = pv;
;           a += pv;
;         }
;         rs += a;
;         if (MODE == 1) {
;           impA[kt] += a;
;           impE[kt] += S[kt][hh][3];
;         }
;       }
;       if (MODE != 1 && !(FX && MODE == 2)) st.l[hh] += rs;
;       if (MODE != 0) {
; #pragma unroll
;         for (int c = 0; c < 2; ++c)
.Lnsa_fast:
	s_waitcnt lgkmcnt(7)
	v_mfma_f32_16x16x32_bf16 v[98:101], v[220:223], v[2:5], 0
	s_waitcnt lgkmcnt(6)
	v_mfma_f32_16x16x32_bf16 v[106:109], v[224:227], v[2:5], 0
	s_waitcnt lgkmcnt(5)
	v_mfma_f32_16x16x32_bf16 v[102:105], v[228:231], v[2:5], 0
	s_waitcnt lgkmcnt(4)
	v_mfma_f32_16x16x32_bf16 v[110:113], v[232:235], v[2:5], 0
	s_waitcnt lgkmcnt(3)
	v_mfma_f32_16x16x32_bf16 v[98:101], v[236:239], v[6:9], v[98:101]
	s_waitcnt lgkmcnt(2)
	v_mfma_f32_16x16x32_bf16 v[106:109], v[240:243], v[6:9], v[106:109]
	s_waitcnt lgkmcnt(1)
	v_mfma_f32_16x16x32_bf16 v[102:105], v[244:247], v[6:9], v[102:105]
	s_waitcnt lgkmcnt(0)
	v_mfma_f32_16x16x32_bf16 v[110:113], v[198:201], v[6:9], v[110:113]
	v_cmp_lt_i32_e32 vcc, 62, v215
	v_mfma_f32_16x16x32_bf16 v[90:93], v[220:223], v[10:13], 0
	v_mfma_f32_16x16x32_bf16 v[94:97], v[224:227], v[10:13], 0
	v_cndmask_b32_e32 v217, v197, v205, vcc
	v_mfma_f32_16x16x32_bf16 v[82:85], v[228:231], v[10:13], 0
	v_mfma_f32_16x16x32_bf16 v[86:89], v[232:235], v[10:13], 0
	v_fmamk_f32 v74, v98, 0x3fb8aa3b, v217
	v_fmamk_f32 v75, v99, 0x3fb8aa3b, v217
	v_mfma_f32_16x16x32_bf16 v[90:93], v[236:239], v[14:17], v[90:93]
	v_fmamk_f32 v76, v100, 0x3fb8aa3b, v217
	v_fmamk_f32 v77, v101, 0x3fb8aa3b, v217
	v_mfma_f32_16x16x32_bf16 v[94:97], v[240:243], v[14:17], v[94:97]
	v_fmamk_f32 v78, v106, 0x3fb8aa3b, v217
	v_fmamk_f32 v79, v107, 0x3fb8aa3b, v217
	v_mfma_f32_16x16x32_bf16 v[82:85], v[244:247], v[14:17], v[82:85]
	v_fmamk_f32 v80, v108, 0x3fb8aa3b, v217
	v_fmamk_f32 v81, v109, 0x3fb8aa3b, v217
	v_mfma_f32_16x16x32_bf16 v[86:89], v[198:201], v[14:17], v[86:89]
	ds_read_b64 v[220:221], v207 offset:8192
	v_fmamk_f32 v164, v102, 0x3fb8aa3b, v217
	ds_read_b64 v[222:223], v208 offset:8192
	v_fmamk_f32 v165, v103, 0x3fb8aa3b, v217
	ds_read_b64 v[224:225], v209 offset:8192
	v_fmamk_f32 v166, v104, 0x3fb8aa3b, v217
	ds_read_b64 v[226:227], v210 offset:8192
	v_fmamk_f32 v167, v105, 0x3fb8aa3b, v217
	ds_read_b64 v[228:229], v207 offset:10240
	v_fmamk_f32 v168, v110, 0x3fb8aa3b, v217
	ds_read_b64 v[230:231], v208 offset:10240
	v_fmamk_f32 v169, v111, 0x3fb8aa3b, v217
	ds_read_b64 v[232:233], v209 offset:10240
	v_fmamk_f32 v170, v112, 0x3fb8aa3b, v217
	ds_read_b64 v[234:235], v210 offset:10240
	v_fmamk_f32 v171, v113, 0x3fb8aa3b, v217
	ds_read_b64 v[236:237], v207 offset:12288
	v_exp_f32_e32 v74, v74
	ds_read_b64 v[238:239], v208 offset:12288
	v_exp_f32_e32 v75, v75
	ds_read_b64 v[240:241], v209 offset:12288
	v_exp_f32_e32 v76, v76
	ds_read_b64 v[242:243], v210 offset:12288
	v_exp_f32_e32 v77, v77
	ds_read_b64 v[244:245], v211 offset:8192
	v_exp_f32_e32 v78, v78
	ds_read_b64 v[246:247], v212 offset:8192
	v_exp_f32_e32 v79, v79
	ds_read_b64 v[198:199], v213 offset:8192
	v_exp_f32_e32 v80, v80
	ds_read_b64 v[200:201], v214 offset:8192
	v_exp_f32_e32 v81, v81
	v_exp_f32_e32 v164, v164
	v_exp_f32_e32 v165, v165
	v_exp_f32_e32 v166, v166
	v_exp_f32_e32 v167, v167
	v_exp_f32_e32 v168, v168
	v_exp_f32_e32 v169, v169
	v_exp_f32_e32 v170, v170
	v_exp_f32_e32 v171, v171
	v_cvt_pk_bf16_f32 v74, v74, v75
	v_cvt_pk_bf16_f32 v75, v76, v77
	v_cvt_pk_bf16_f32 v76, v78, v79
	v_cvt_pk_bf16_f32 v77, v80, v81
	v_cvt_pk_bf16_f32 v78, v164, v165
	v_cvt_pk_bf16_f32 v79, v166, v167
	v_cvt_pk_bf16_f32 v80, v168, v169
	v_cvt_pk_bf16_f32 v81, v170, v171
	s_cmp_lg_u32 s101, 0
	s_cbranch_scc1 .Lnsa_fast_defer
	s_waitcnt lgkmcnt(0)
	v_fmamk_f32 v164, v90, 0x3fb8aa3b, v217
	v_fmamk_f32 v165, v91, 0x3fb8aa3b, v217
	v_fmamk_f32 v166, v92, 0x3fb8aa3b, v217
	v_mfma_f32_16x16x32_bf16 v[50:53], v[220:223], v[74:77], v[50:53]
	v_fmamk_f32 v167, v93, 0x3fb8aa3b, v217
	s_mov_b32 s10, s8
	s_mov_b32 s11, s8
	s_mov_b32 s9, s8
	v_mfma_f32_16x16x32_bf16 v[42:45], v[228:231], v[74:77], v[42:45]
	v_mov_b64_e32 v[92:93], s[10:11]
	v_mov_b64_e32 v[90:91], s[8:9]
	v_fmamk_f32 v168, v94, 0x3fb8aa3b, v217
	v_fmamk_f32 v169, v95, 0x3fb8aa3b, v217
	v_mfma_f32_16x16x32_bf16 v[38:41], v[236:239], v[74:77], v[38:41]
	v_fmamk_f32 v170, v96, 0x3fb8aa3b, v217
	v_fmamk_f32 v171, v97, 0x3fb8aa3b, v217
	v_fmamk_f32 v172, v82, 0x3fb8aa3b, v217
	v_fmamk_f32 v173, v83, 0x3fb8aa3b, v217
	v_mfma_f32_16x16x32_bf16 v[34:37], v[244:247], v[74:77], v[34:37]
	v_fmamk_f32 v174, v84, 0x3fb8aa3b, v217
	v_fmamk_f32 v175, v85, 0x3fb8aa3b, v217
	v_fmamk_f32 v176, v86, 0x3fb8aa3b, v217
	v_fmamk_f32 v177, v87, 0x3fb8aa3b, v217
	v_mfma_f32_16x16x32_bf16 v[50:53], v[224:227], v[78:81], v[50:53]
	v_fmamk_f32 v178, v88, 0x3fb8aa3b, v217
	v_fmamk_f32 v179, v89, 0x3fb8aa3b, v217
	v_exp_f32_e32 v164, v164
	v_exp_f32_e32 v165, v165
	v_mfma_f32_16x16x32_bf16 v[42:45], v[232:235], v[78:81], v[42:45]
	v_exp_f32_e32 v166, v166
	v_exp_f32_e32 v167, v167
	v_exp_f32_e32 v168, v168
	v_exp_f32_e32 v169, v169
	v_mfma_f32_16x16x32_bf16 v[38:41], v[240:243], v[78:81], v[38:41]
	v_exp_f32_e32 v170, v170
	v_exp_f32_e32 v171, v171
	v_exp_f32_e32 v172, v172
	v_exp_f32_e32 v173, v173
	v_mfma_f32_16x16x32_bf16 v[34:37], v[198:201], v[78:81], v[34:37]
	v_exp_f32_e32 v174, v174
	v_exp_f32_e32 v175, v175
	v_exp_f32_e32 v176, v176
	v_exp_f32_e32 v177, v177
	v_mfma_f32_16x16x32_bf16 v[54:57], v[90:93], v[74:77], v[54:57]
	v_exp_f32_e32 v178, v178
	v_exp_f32_e32 v179, v179
	v_cvt_pk_bf16_f32 v82, v164, v165
	v_cvt_pk_bf16_f32 v83, v166, v167
	v_mfma_f32_16x16x32_bf16 v[54:57], v[90:93], v[78:81], v[54:57]
	v_cvt_pk_bf16_f32 v84, v168, v169
	v_cvt_pk_bf16_f32 v85, v170, v171
	v_cvt_pk_bf16_f32 v86, v172, v173
	v_cvt_pk_bf16_f32 v87, v174, v175
	v_cvt_pk_bf16_f32 v88, v176, v177
	v_cvt_pk_bf16_f32 v89, v178, v179
	s_nop 1
	v_mfma_f32_16x16x32_bf16 v[30:33], v[220:223], v[82:85], v[30:33]
	v_mfma_f32_16x16x32_bf16 v[26:29], v[228:231], v[82:85], v[26:29]
	v_mfma_f32_16x16x32_bf16 v[22:25], v[236:239], v[82:85], v[22:25]
	v_mfma_f32_16x16x32_bf16 v[18:21], v[244:247], v[82:85], v[18:21]
	v_mfma_f32_16x16x32_bf16 v[30:33], v[224:227], v[86:89], v[30:33]
	v_mfma_f32_16x16x32_bf16 v[26:29], v[232:235], v[86:89], v[26:29]
	v_mfma_f32_16x16x32_bf16 v[22:25], v[240:243], v[86:89], v[22:25]
	v_mfma_f32_16x16x32_bf16 v[18:21], v[198:201], v[86:89], v[18:21]
	v_mfma_f32_16x16x32_bf16 v[46:49], v[90:93], v[82:85], v[46:49]
	v_mfma_f32_16x16x32_bf16 v[46:49], v[90:93], v[86:89], v[46:49]
	s_branch .LBB0_667
.Lnsa_fast_defer:
	s_mov_b32 s100, 1
	s_branch .LBB0_667

; DI f32x4 mfma16(bf16x8 a, bf16x8 b, f32x4 c) { return __builtin_amdgcn_mfma_f32_16x16x32_bf16(a, b, c, 0, 0, 0); }
; template <int MODE, bool FX>
; DI void attn_compute(const int lane, const bf16_t* Ks, const bf16_t* Vs, const bf16x8 (&qf)[2][2], AttnSt& st, const float (&invl)[2],
;                      int lo, int hi, float (&impA)[4], float (&impE)[4], const float CL) {
;     ...
;   if (MODE != 0) {
; #pragma unroll
;     for (int dt = 0; dt < 4; ++dt) {
;       const int row = dt * 16 + col;
;       const int sw = (row >> 1) & 7;
; #pragma unroll
;       for (int c = 0; c < 2; ++c) {
;         uint2 a = *(const uint2*)(Vs + row * 64 + (((4 * c + (quad >> 1)) ^ sw) << 3) + (quad & 1) * 4);
;         uint2 b = *(const uint2*)(Vs + row * 64 + (((4 * c + 2 + (quad >> 1)) ^ sw) << 3) + (quad & 1) * 4);
;         bf16x8 vf = mk8(a.x, a.y, b.x, b.y);
; #pragma unroll
;         for (int hh = 0; hh < 2; ++hh) st.O[hh][dt] = mfma16(vf, pf[hh][c], st.O[hh][dt]);
;       }
;     }
;     if (FX && MODE == 2) {
;       const bf16x8 ones = mk8(0x3F803F80u, 0x3F803F80u, 0x3F803F80u, 0x3F803F80u);
; #pragma unroll
;       for (int c = 0; c < 2; ++c)
; #pragma unroll
;         for (int hh = 0; hh < 2; ++hh) st.L[hh] = mfma16(ones, pf[hh][c], st.L[hh]);
;     }
; template <bool FX>
; DI void nsa_tile(const Params& p, int b, int g, int tile, bf16_t* lds, const float CL) {
;     ...
;       for (int s = 0; s <= cur; ++s) {
;         __syncthreads();
;         tile64_sstore(tid, Ks, rk0, rk1);
;         tile64_sstore(tid, Vs, rv0, rv1);
;         __syncthreads();
;         if (s < cur) {
;           tile64_gload(tid, rk0, rk1, kb + (size_t)(s + 1) * 64 * ZS, ZS);
;           tile64_gload(tid, rv0, rv1, vsT + (s + 1) * 64, TS);
;         }
;         uint32_t wsel = (s < 32) ? sw0 : (s < 64) ? sw1 : (s < 96) ? sw2 : sw3;
;         bool sel = (wsel >> (s & 31)) & 1u;
;         int hi = sel ? (tok - s * 64) : -1;
;         if (__any(hi >= 0)) attn_compute<2, FX>(lane, Ks, Vs, qf, st, invl, 0, hi, dA, dE, CL);
.LBB0_668:
	s_add_i32 s68, s68, 1
	s_waitcnt vmcnt(0) lgkmcnt(0)
	s_barrier
	s_cmp_ge_u32 s68, s25
	s_cbranch_scc1 .LBB0_670
	s_lshl_b64 s[2:3], s[28:29], 1
	s_add_u32 s2, s12, s2
	s_addc_u32 s3, s13, s3
	v_lshl_add_u64 v[66:67], v[138:139], 1, s[2:3]
	v_lshl_add_u64 v[68:69], v[142:143], 1, s[2:3]
	v_lshl_add_u64 v[66:67], v[66:67], 0, v[202:203]
	v_lshl_add_u64 v[70:71], v[68:69], 0, v[202:203]
	s_mov_b32 m0, s76
	s_nop 0
	global_load_lds_dwordx4 v[158:159], off
	s_add_u32 m0, s76, 0x1000
	s_nop 0
	global_load_lds_dwordx4 v[160:161], off
	s_add_u32 m0, s76, 0x2000
	s_nop 0
	global_load_lds_dwordx4 v[66:67], off
	s_add_u32 m0, s76, 0x3000
	s_nop 0
	global_load_lds_dwordx4 v[70:71], off
	s_xor_b32 s76, s76, 0xc000
.LBB0_670:
	s_cmp_eq_u32 s100, 0
	s_cbranch_scc1 .Lnsa_nopend
	s_waitcnt lgkmcnt(0)
	v_fmamk_f32 v164, v90, 0x3fb8aa3b, v217
	v_fmamk_f32 v165, v91, 0x3fb8aa3b, v217
	v_fmamk_f32 v166, v92, 0x3fb8aa3b, v217
	v_mfma_f32_16x16x32_bf16 v[50:53], v[220:223], v[74:77], v[50:53]
	v_fmamk_f32 v167, v93, 0x3fb8aa3b, v217
	s_mov_b32 s10, s8
	s_mov_b32 s11, s8
	s_mov_b32 s9, s8
	v_mfma_f32_16x16x32_bf16 v[42:45], v[228:231], v[74:77], v[42:45]
	v_mov_b64_e32 v[92:93], s[10:11]
	v_mov_b64_e32 v[90:91], s[8:9]
	v_fmamk_f32 v168, v94, 0x3fb8aa3b, v217
	v_fmamk_f32 v169, v95, 0x3fb8aa3b, v217
	v_mfma_f32_16x16x32_bf16 v[38:41], v[236:239], v[74:77], v[38:41]
	v_fmamk_f32 v170, v96, 0x3fb8aa3b, v217
	v_fmamk_f32 v171, v97, 0x3fb8aa3b, v217
	v_fmamk_f32 v172, v82, 0x3fb8aa3b, v217
	v_fmamk_f32 v173, v83, 0x3fb8aa3b, v217
	v_mfma_f32_16x16x32_bf16 v[34:37], v[244:247], v[74:77], v[34:37]
	v_fmamk_f32 v174, v84, 0x3fb8aa3b, v217
	v_fmamk_f32 v175, v85, 0x3fb8aa3b, v217
	v_fmamk_f32 v176, v86, 0x3fb8aa3b, v217
	v_fmamk_f32 v177, v87, 0x3fb8aa3b, v217
	v_mfma_f32_16x16x32_bf16 v[50:53], v[224:227], v[78:81], v[50:53]
	v_fmamk_f32 v178, v88, 0x3fb8aa3b, v217
	v_fmamk_f32 v179, v89, 0x3fb8aa3b, v217
	v_exp_f32_e32 v164, v164
	v_exp_f32_e32 v165, v165
	v_mfma_f32_16x16x32_bf16 v[42:45], v[232:235], v[78:81], v[42:45]
	v_exp_f32_e32 v166, v166
	v_exp_f32_e32 v167, v167
	v_exp_f32_e32 v168, v168
	v_exp_f32_e32 v169, v169
	v_mfma_f32_16x16x32_bf16 v[38:41], v[240:243], v[78:81], v[38:41]
	v_exp_f32_e32 v170, v170
	v_exp_f32_e32 v171, v171
	v_exp_f32_e32 v172, v172
	v_exp_f32_e32 v173, v173
	v_mfma_f32_16x16x32_bf16 v[34:37], v[198:201], v[78:81], v[34:37]
	v_exp_f32_e32 v174, v174
	v_exp_f32_e32 v175, v175
	v_exp_f32_e32 v176, v176
	v_exp_f32_e32 v177, v177
	v_mfma_f32_16x16x32_bf16 v[54:57], v[90:93], v[74:77], v[54:57]
	v_exp_f32_e32 v178, v178
	v_exp_f32_e32 v179, v179
	v_cvt_pk_bf16_f32 v82, v164, v165
	v_cvt_pk_bf16_f32 v83, v166, v167
	v_mfma_f32_16x16x32_bf16 v[54:57], v[90:93], v[78:81], v[54:57]
	v_cvt_pk_bf16_f32 v84, v168, v169
	v_cvt_pk_bf16_f32 v85, v170, v171
	v_cvt_pk_bf16_f32 v86, v172, v173
	v_cvt_pk_bf16_f32 v87, v174, v175
	v_cvt_pk_bf16_f32 v88, v176, v177
	v_cvt_pk_bf16_f32 v89, v178, v179
	s_nop 1
	v_mfma_f32_16x16x32_bf16 v[30:33], v[220:223], v[82:85], v[30:33]
	v_mfma_f32_16x16x32_bf16 v[26:29], v[228:231], v[82:85], v[26:29]
	v_mfma_f32_16x16x32_bf16 v[22:25], v[236:239], v[82:85], v[22:25]
	v_mfma_f32_16x16x32_bf16 v[18:21], v[244:247], v[82:85], v[18:21]
	v_mfma_f32_16x16x32_bf16 v[30:33], v[224:227], v[86:89], v[30:33]
	v_mfma_f32_16x16x32_bf16 v[26:29], v[232:235], v[86:89], v[26:29]
	v_mfma_f32_16x16x32_bf16 v[22:25], v[240:243], v[86:89], v[22:25]
	v_mfma_f32_16x16x32_bf16 v[18:21], v[198:201], v[86:89], v[18:21]
	v_mfma_f32_16x16x32_bf16 v[46:49], v[90:93], v[82:85], v[46:49]
	v_mfma_f32_16x16x32_bf16 v[46:49], v[90:93], v[86:89], v[46:49]
	s_mov_b32 s100, 0

; DI float bf2f(bf16_t h) { return __uint_as_float(((unsigned)h) << 16); }
; DI float sigmoidf(float x) { return __builtin_amdgcn_rcpf(1.f + __expf(-x)); }
; DI f32x4 mfma16(bf16x8 a, bf16x8 b, f32x4 c) { return __builtin_amdgcn_mfma_f32_16x16x32_bf16(a, b, c, 0, 0, 0); }
; template <int MODE, bool FX>
; DI void attn_compute(const int lane, const bf16_t* Ks, const bf16_t* Vs, const bf16x8 (&qf)[2][2], AttnSt& st, const float (&invl)[2],
;                      int lo, int hi, float (&impA)[4], float (&impE)[4], const float CL) {
;     ...
;   if (MODE != 0) {
; #pragma unroll
;     for (int dt = 0; dt < 4; ++dt) {
;       const int row = dt * 16 + col;
;       const int sw = (row >> 1) & 7;
; #pragma unroll
;       for (int c = 0; c < 2; ++c) {
;         uint2 a = *(const uint2*)(Vs + row * 64 + (((4 * c + (quad >> 1)) ^ sw) << 3) + (quad & 1) * 4);
;         uint2 b = *(const uint2*)(Vs + row * 64 + (((4 * c + 2 + (quad >> 1)) ^ sw) << 3) + (quad & 1) * 4);
;         bf16x8 vf = mk8(a.x, a.y, b.x, b.y);
; #pragma unroll
;         for (int hh = 0; hh < 2; ++hh) st.O[hh][dt] = mfma16(vf, pf[hh][c], st.O[hh][dt]);
;       }
;     }
;     if (FX && MODE == 2) {
;       const bf16x8 ones = mk8(0x3F803F80u, 0x3F803F80u, 0x3F803F80u, 0x3F803F80u);
; #pragma unroll
;       for (int c = 0; c < 2; ++c)
; #pragma unroll
;         for (int hh = 0; hh < 2; ++hh) st.L[hh] = mfma16(ones, pf[hh][c], st.L[hh]);
;     }
; template <bool FX>
; DI void nsa_tile(const Params& p, int b, int g, int tile, bf16_t* lds, const float CL) {
;     ...
;     {
;       float sc[2];
; #pragma unroll
;       for (int h = 0; h < 2; ++h) {
;         float l;
;         if (FX) {
;           l = st.L[h][0];
;         } else {
;           l = st.l[h];
;           l += shx(l, 16, lane);
;           l += shx(l, 32, lane);
;         }
;         sc[h] = (l > 0.f) ? sigmoidf(bf2f(ztok[C_GT + 1 * 8 + g * 4 + hp * 2 + h])) / l : 0.f;
;       }
;       nsa_flush<false>(quad, otok + hp * 128, st, sc);
.LBB0_675:
	s_cmp_eq_u32 s100, 0
	s_cbranch_scc1 .Lnsa_noflush
	s_waitcnt lgkmcnt(0)
	v_fmamk_f32 v164, v90, 0x3fb8aa3b, v217
	v_fmamk_f32 v165, v91, 0x3fb8aa3b, v217
	v_fmamk_f32 v166, v92, 0x3fb8aa3b, v217
	v_mfma_f32_16x16x32_bf16 v[50:53], v[220:223], v[74:77], v[50:53]
	v_fmamk_f32 v167, v93, 0x3fb8aa3b, v217
	s_mov_b32 s10, s8
	s_mov_b32 s11, s8
	s_mov_b32 s9, s8
	v_mfma_f32_16x16x32_bf16 v[42:45], v[228:231], v[74:77], v[42:45]
	v_mov_b64_e32 v[92:93], s[10:11]
	v_mov_b64_e32 v[90:91], s[8:9]
	v_fmamk_f32 v168, v94, 0x3fb8aa3b, v217
	v_fmamk_f32 v169, v95, 0x3fb8aa3b, v217
	v_mfma_f32_16x16x32_bf16 v[38:41], v[236:239], v[74:77], v[38:41]
	v_fmamk_f32 v170, v96, 0x3fb8aa3b, v217
	v_fmamk_f32 v171, v97, 0x3fb8aa3b, v217
	v_fmamk_f32 v172, v82, 0x3fb8aa3b, v217
	v_fmamk_f32 v173, v83, 0x3fb8aa3b, v217
	v_mfma_f32_16x16x32_bf16 v[34:37], v[244:247], v[74:77], v[34:37]
	v_fmamk_f32 v174, v84, 0x3fb8aa3b, v217
	v_fmamk_f32 v175, v85, 0x3fb8aa3b, v217
	v_fmamk_f32 v176, v86, 0x3fb8aa3b, v217
	v_fmamk_f32 v177, v87, 0x3fb8aa3b, v217
	v_mfma_f32_16x16x32_bf16 v[50:53], v[224:227], v[78:81], v[50:53]
	v_fmamk_f32 v178, v88, 0x3fb8aa3b, v217
	v_fmamk_f32 v179, v89, 0x3fb8aa3b, v217
	v_exp_f32_e32 v164, v164
	v_exp_f32_e32 v165, v165
	v_mfma_f32_16x16x32_bf16 v[42:45], v[232:235], v[78:81], v[42:45]
	v_exp_f32_e32 v166, v166
	v_exp_f32_e32 v167, v167
	v_exp_f32_e32 v168, v168
	v_exp_f32_e32 v169, v169
	v_mfma_f32_16x16x32_bf16 v[38:41], v[240:243], v[78:81], v[38:41]
	v_exp_f32_e32 v170, v170
	v_exp_f32_e32 v171, v171
	v_exp_f32_e32 v172, v172
	v_exp_f32_e32 v173, v173
	v_mfma_f32_16x16x32_bf16 v[34:37], v[198:201], v[78:81], v[34:37]
	v_exp_f32_e32 v174, v174
	v_exp_f32_e32 v175, v175
	v_exp_f32_e32 v176, v176
	v_exp_f32_e32 v177, v177
	v_mfma_f32_16x16x32_bf16 v[54:57], v[90:93], v[74:77], v[54:57]
	v_exp_f32_e32 v178, v178
	v_exp_f32_e32 v179, v179
	v_cvt_pk_bf16_f32 v82, v164, v165
	v_cvt_pk_bf16_f32 v83, v166, v167
	v_mfma_f32_16x16x32_bf16 v[54:57], v[90:93], v[78:81], v[54:57]
	v_cvt_pk_bf16_f32 v84, v168, v169
	v_cvt_pk_bf16_f32 v85, v170, v171
	v_cvt_pk_bf16_f32 v86, v172, v173
	v_cvt_pk_bf16_f32 v87, v174, v175
	v_cvt_pk_bf16_f32 v88, v176, v177
	v_cvt_pk_bf16_f32 v89, v178, v179
	s_nop 1
	v_mfma_f32_16x16x32_bf16 v[30:33], v[220:223], v[82:85], v[30:33]
	v_mfma_f32_16x16x32_bf16 v[26:29], v[228:231], v[82:85], v[26:29]
	v_mfma_f32_16x16x32_bf16 v[22:25], v[236:239], v[82:85], v[22:25]
	v_mfma_f32_16x16x32_bf16 v[18:21], v[244:247], v[82:85], v[18:21]
	v_mfma_f32_16x16x32_bf16 v[30:33], v[224:227], v[86:89], v[30:33]
	v_mfma_f32_16x16x32_bf16 v[26:29], v[232:235], v[86:89], v[26:29]
	v_mfma_f32_16x16x32_bf16 v[22:25], v[240:243], v[86:89], v[22:25]
	v_mfma_f32_16x16x32_bf16 v[18:21], v[198:201], v[86:89], v[18:21]
	v_mfma_f32_16x16x32_bf16 v[46:49], v[90:93], v[82:85], v[46:49]
	v_mfma_f32_16x16x32_bf16 v[46:49], v[90:93], v[86:89], v[46:49]
	s_mov_b32 s100, 0
	s_nop 7
	s_nop 7
